# a19 + ret_out: gate loads issued at item top into v226-241 (epilogue copies), P packed in place
# baseline (speedup 1.0000x reference)
.LBB0_864:
	s_or_b64 exec, exec, s[40:41]
	v_lshl_add_u64 v[32:33], v[124:125], 0, s[0:1]
	v_lshl_add_u64 v[32:33], v[32:33], 0, v[126:127]
	v_lshlrev_b64 v[32:33], 1, v[32:33]
	v_lshl_add_u64 v[34:35], s[16:17], 0, v[32:33]
	s_waitcnt lgkmcnt(0)
	s_barrier
	v_mov_b32_e32 v40, v226
	v_mov_b32_e32 v41, v227
	v_mov_b32_e32 v42, v228
	v_mov_b32_e32 v43, v229
	v_mov_b32_e32 v44, v230
	v_mov_b32_e32 v45, v231
	ds_read_b32 v37, v130
	v_mov_b32_e32 v46, v232
	v_mov_b32_e32 v47, v233
	v_mov_b32_e32 v38, v234
	v_mov_b32_e32 v39, v235
	v_mov_b32_e32 v88, v236
	v_mov_b32_e32 v89, v237
	v_lshl_add_u64 v[32:33], s[20:21], 0, v[32:33]
	s_mov_b32 s8, s34
	s_waitcnt lgkmcnt(0)
	v_add_f32_e32 v36, v36, v37
	v_fmamk_f32 v36, v36, 0x3c000000, v140
	v_mul_f32_e32 v37, 0x4b800000, v36
	v_cmp_gt_f32_e32 vcc, s44, v36
	v_lshlrev_b32_e32 v90, 16, v40
	v_cndmask_b32_e32 v36, v36, v37, vcc
	v_rsq_f32_e32 v36, v36
	v_and_b32_e32 v91, 0xffff0000, v40
	v_lshlrev_b32_e32 v40, 16, v41
	v_and_b32_e32 v41, 0xffff0000, v41
	v_mul_f32_e32 v37, 0x45800000, v36
	v_cndmask_b32_e32 v36, v36, v37, vcc
	v_lshlrev_b32_e32 v92, 16, v42
	v_and_b32_e32 v93, 0xffff0000, v42
	v_lshlrev_b32_e32 v42, 16, v43
	v_and_b32_e32 v43, 0xffff0000, v43
	v_mul_f32_e32 v37, 0xbfb8aa3b, v90
	v_mul_f32_e32 v96, 0xbfb8aa3b, v91
	v_mul_f32_e32 v97, 0xbfb8aa3b, v40
	v_mul_f32_e32 v98, 0xbfb8aa3b, v41
	v_lshlrev_b32_e32 v94, 16, v44
	v_mul_f32_e32 v99, 0xbfb8aa3b, v92
	v_mul_f32_e32 v100, 0xbfb8aa3b, v93
	v_mul_f32_e32 v101, 0xbfb8aa3b, v42
	v_mul_f32_e32 v102, 0xbfb8aa3b, v43
	v_exp_f32_e32 v37, v37
	v_exp_f32_e32 v96, v96
	v_exp_f32_e32 v97, v97
	v_exp_f32_e32 v98, v98
	v_mul_f32_e32 v103, 0xbfb8aa3b, v94
	v_exp_f32_e32 v99, v99
	v_exp_f32_e32 v100, v100
	v_exp_f32_e32 v101, v101
	v_exp_f32_e32 v102, v102
	v_and_b32_e32 v95, 0xffff0000, v44
	v_lshlrev_b32_e32 v44, 16, v45
	v_and_b32_e32 v45, 0xffff0000, v45
	v_exp_f32_e32 v103, v103
	v_mul_f32_e32 v128, 0xbfb8aa3b, v45
	v_exp_f32_e32 v129, v128
	v_add_f32_e32 v37, 1.0, v37
	v_add_f32_e32 v128, 1.0, v96
	v_add_f32_e32 v142, 1.0, v97
	v_add_f32_e32 v143, 1.0, v98
	v_add_f32_e32 v144, 1.0, v99
	v_add_f32_e32 v145, 1.0, v100
	v_add_f32_e32 v146, 1.0, v101
	v_add_f32_e32 v147, 1.0, v102
	v_rcp_f32_e32 v96, v37
	v_rcp_f32_e32 v97, v128
	v_rcp_f32_e32 v98, v142
	v_rcp_f32_e32 v99, v143
	v_add_f32_e32 v148, 1.0, v103
	v_rcp_f32_e32 v100, v144
	v_rcp_f32_e32 v101, v145
	v_rcp_f32_e32 v102, v146
	v_rcp_f32_e32 v103, v147
	v_mul_f32_e32 v126, 0xbfb8aa3b, v95
	v_mul_f32_e32 v127, 0xbfb8aa3b, v44
	v_exp_f32_e32 v126, v126
	v_exp_f32_e32 v127, v127
	v_pk_mul_f32 v[90:91], v[96:97], v[90:91]
	v_pk_mul_f32 v[40:41], v[98:99], v[40:41]
	v_pk_mul_f32 v[92:93], v[100:101], v[92:93]
	v_pk_mul_f32 v[42:43], v[102:103], v[42:43]
	v_pk_mul_f32 v[16:17], v[16:17], v[90:91]
	v_pk_mul_f32 v[18:19], v[18:19], v[40:41]
	v_pk_mul_f32 v[20:21], v[20:21], v[92:93]
	v_pk_mul_f32 v[22:23], v[22:23], v[42:43]
	v_pk_mul_f32 v[16:17], v[36:37], v[16:17] op_sel_hi:[0,1]
	v_pk_mul_f32 v[18:19], v[36:37], v[18:19] op_sel_hi:[0,1]
	v_pk_mul_f32 v[20:21], v[36:37], v[20:21] op_sel_hi:[0,1]
	v_pk_mul_f32 v[22:23], v[36:37], v[22:23] op_sel_hi:[0,1]
	v_cvt_pk_bf16_f32 v16, v16, v17
	v_cvt_pk_bf16_f32 v17, v18, v19
	v_add_f32_e32 v149, 1.0, v126
	v_add_f32_e32 v150, 1.0, v127
	v_cvt_pk_bf16_f32 v18, v20, v21
	v_cvt_pk_bf16_f32 v19, v22, v23
	global_store_dwordx2 v[32:33], v[16:17], off
	global_store_dwordx2 v[32:33], v[18:19], off offset:16
	v_add_f32_e32 v16, 1.0, v129
	v_rcp_f32_e32 v126, v148
	v_rcp_f32_e32 v127, v149
	v_rcp_f32_e32 v128, v150
	v_rcp_f32_e32 v129, v16
	v_mov_b32_e32 v20, v238
	v_mov_b32_e32 v21, v239
	v_pk_mul_f32 v[94:95], v[126:127], v[94:95]
	v_lshlrev_b32_e32 v22, 16, v47
	v_pk_mul_f32 v[18:19], v[128:129], v[44:45]
	v_pk_mul_f32 v[16:17], v[24:25], v[94:95]
	v_pk_mul_f32 v[18:19], v[26:27], v[18:19]
	v_pk_mul_f32 v[16:17], v[36:37], v[16:17] op_sel_hi:[0,1]
	v_pk_mul_f32 v[18:19], v[36:37], v[18:19] op_sel_hi:[0,1]
	v_cvt_pk_bf16_f32 v16, v16, v17
	v_cvt_pk_bf16_f32 v17, v18, v19
	global_store_dwordx2 v[32:33], v[16:17], off offset:32
	v_lshlrev_b32_e32 v16, 16, v46
	v_mul_f32_e32 v17, 0xbfb8aa3b, v16
	v_exp_f32_e32 v18, v17
	v_and_b32_e32 v17, 0xffff0000, v46
	v_mul_f32_e32 v19, 0xbfb8aa3b, v17
	v_exp_f32_e32 v19, v19
	v_and_b32_e32 v23, 0xffff0000, v47
	v_add_f32_e32 v18, 1.0, v18
	v_mul_f32_e32 v24, 0xbfb8aa3b, v22
	v_add_f32_e32 v19, 1.0, v19
	v_mul_f32_e32 v25, 0xbfb8aa3b, v23
	v_rcp_f32_e32 v18, v18
	v_rcp_f32_e32 v19, v19
	v_exp_f32_e32 v24, v24
	v_exp_f32_e32 v25, v25
	s_andn2_b64 vcc, exec, s[38:39]
	v_pk_mul_f32 v[16:17], v[18:19], v[16:17]
	v_add_f32_e32 v18, 1.0, v24
	v_add_f32_e32 v19, 1.0, v25
	v_rcp_f32_e32 v18, v18
	v_rcp_f32_e32 v19, v19
	v_pk_mul_f32 v[16:17], v[28:29], v[16:17]
	v_pk_mul_f32 v[18:19], v[18:19], v[22:23]
	s_nop 0
	v_pk_mul_f32 v[18:19], v[30:31], v[18:19]
	v_pk_mul_f32 v[16:17], v[36:37], v[16:17] op_sel_hi:[0,1]
	v_pk_mul_f32 v[18:19], v[36:37], v[18:19] op_sel_hi:[0,1]
	v_cvt_pk_bf16_f32 v16, v16, v17
	v_cvt_pk_bf16_f32 v17, v18, v19
	v_mov_b32_e32 v18, v240
	v_mov_b32_e32 v19, v241
	v_lshlrev_b32_e32 v22, 16, v38
	v_and_b32_e32 v23, 0xffff0000, v38
	v_mul_f32_e32 v24, 0xbfb8aa3b, v22
	v_mul_f32_e32 v25, 0xbfb8aa3b, v23
	v_exp_f32_e32 v24, v24
	v_exp_f32_e32 v25, v25
	global_store_dwordx2 v[32:33], v[16:17], off offset:48
	v_add_f32_e32 v16, 1.0, v24
	v_add_f32_e32 v17, 1.0, v25
	v_lshlrev_b32_e32 v24, 16, v39
	v_and_b32_e32 v25, 0xffff0000, v39
	v_mul_f32_e32 v26, 0xbfb8aa3b, v24
	v_mul_f32_e32 v27, 0xbfb8aa3b, v25
	v_rcp_f32_e32 v16, v16
	v_rcp_f32_e32 v17, v17
	v_exp_f32_e32 v26, v26
	v_exp_f32_e32 v27, v27
	v_pk_mul_f32 v[16:17], v[16:17], v[22:23]
	v_add_f32_e32 v22, 1.0, v26
	v_add_f32_e32 v23, 1.0, v27
	v_rcp_f32_e32 v22, v22
	v_rcp_f32_e32 v23, v23
	v_pk_mul_f32 v[0:1], v[0:1], v[16:17]
	v_pk_mul_f32 v[16:17], v[22:23], v[24:25]
	s_nop 0
	v_pk_mul_f32 v[2:3], v[2:3], v[16:17]
	v_pk_mul_f32 v[0:1], v[36:37], v[0:1] op_sel_hi:[0,1]
	v_pk_mul_f32 v[2:3], v[36:37], v[2:3] op_sel_hi:[0,1]
	v_cvt_pk_bf16_f32 v0, v0, v1
	v_cvt_pk_bf16_f32 v1, v2, v3
	v_lshlrev_b32_e32 v2, 16, v88
	v_and_b32_e32 v3, 0xffff0000, v88
	v_mul_f32_e32 v16, 0xbfb8aa3b, v2
	v_mul_f32_e32 v17, 0xbfb8aa3b, v3
	v_exp_f32_e32 v16, v16
	v_exp_f32_e32 v17, v17
	global_store_dwordx2 v[32:33], v[0:1], off offset:64
	v_add_f32_e32 v0, 1.0, v16
	v_add_f32_e32 v1, 1.0, v17
	v_lshlrev_b32_e32 v16, 16, v89
	v_and_b32_e32 v17, 0xffff0000, v89
	v_mul_f32_e32 v22, 0xbfb8aa3b, v16
	v_mul_f32_e32 v23, 0xbfb8aa3b, v17
	v_rcp_f32_e32 v0, v0
	v_rcp_f32_e32 v1, v1
	v_exp_f32_e32 v22, v22
	v_exp_f32_e32 v23, v23
	v_pk_mul_f32 v[0:1], v[0:1], v[2:3]
	v_add_f32_e32 v2, 1.0, v22
	v_add_f32_e32 v3, 1.0, v23
	v_rcp_f32_e32 v2, v2
	v_rcp_f32_e32 v3, v3
	v_pk_mul_f32 v[0:1], v[4:5], v[0:1]
	v_pk_mul_f32 v[2:3], v[2:3], v[16:17]
	s_nop 0
	v_pk_mul_f32 v[2:3], v[6:7], v[2:3]
	v_pk_mul_f32 v[0:1], v[36:37], v[0:1] op_sel_hi:[0,1]
	v_pk_mul_f32 v[2:3], v[36:37], v[2:3] op_sel_hi:[0,1]
	v_cvt_pk_bf16_f32 v0, v0, v1
	v_cvt_pk_bf16_f32 v1, v2, v3
	v_lshlrev_b32_e32 v2, 16, v20
	v_and_b32_e32 v3, 0xffff0000, v20
	v_mul_f32_e32 v4, 0xbfb8aa3b, v2
	v_mul_f32_e32 v5, 0xbfb8aa3b, v3
	v_exp_f32_e32 v4, v4
	v_exp_f32_e32 v5, v5
	global_store_dwordx2 v[32:33], v[0:1], off offset:80
	v_add_f32_e32 v0, 1.0, v4
	v_add_f32_e32 v1, 1.0, v5
	v_lshlrev_b32_e32 v4, 16, v21
	v_and_b32_e32 v5, 0xffff0000, v21
	v_mul_f32_e32 v6, 0xbfb8aa3b, v4
	v_mul_f32_e32 v7, 0xbfb8aa3b, v5
	v_rcp_f32_e32 v0, v0
	v_rcp_f32_e32 v1, v1
	v_exp_f32_e32 v6, v6
	v_exp_f32_e32 v7, v7
	v_pk_mul_f32 v[0:1], v[0:1], v[2:3]
	v_add_f32_e32 v2, 1.0, v6
	v_add_f32_e32 v3, 1.0, v7
	v_rcp_f32_e32 v2, v2
	v_rcp_f32_e32 v3, v3
	v_pk_mul_f32 v[0:1], v[8:9], v[0:1]
	v_pk_mul_f32 v[2:3], v[2:3], v[4:5]
	s_nop 0
	v_pk_mul_f32 v[2:3], v[10:11], v[2:3]
	v_pk_mul_f32 v[0:1], v[36:37], v[0:1] op_sel_hi:[0,1]
	v_pk_mul_f32 v[2:3], v[36:37], v[2:3] op_sel_hi:[0,1]
	v_cvt_pk_bf16_f32 v0, v0, v1
	v_cvt_pk_bf16_f32 v1, v2, v3
	v_lshlrev_b32_e32 v2, 16, v18
	v_and_b32_e32 v3, 0xffff0000, v18
	v_mul_f32_e32 v4, 0xbfb8aa3b, v2
	v_mul_f32_e32 v5, 0xbfb8aa3b, v3
	v_exp_f32_e32 v4, v4
	v_exp_f32_e32 v5, v5
	global_store_dwordx2 v[32:33], v[0:1], off offset:96
	v_add_f32_e32 v0, 1.0, v4
	v_add_f32_e32 v1, 1.0, v5
	v_lshlrev_b32_e32 v4, 16, v19
	v_and_b32_e32 v5, 0xffff0000, v19
	v_mul_f32_e32 v6, 0xbfb8aa3b, v4
	v_mul_f32_e32 v7, 0xbfb8aa3b, v5
	v_rcp_f32_e32 v0, v0
	v_rcp_f32_e32 v1, v1
	v_exp_f32_e32 v6, v6
	v_exp_f32_e32 v7, v7
	v_pk_mul_f32 v[0:1], v[0:1], v[2:3]
	v_add_f32_e32 v2, 1.0, v6
	v_add_f32_e32 v3, 1.0, v7
	v_rcp_f32_e32 v2, v2
	v_rcp_f32_e32 v3, v3
	v_pk_mul_f32 v[0:1], v[12:13], v[0:1]
	v_pk_mul_f32 v[2:3], v[2:3], v[4:5]
	s_nop 0
	v_pk_mul_f32 v[2:3], v[14:15], v[2:3]
	v_pk_mul_f32 v[0:1], v[36:37], v[0:1] op_sel_hi:[0,1]
	v_pk_mul_f32 v[2:3], v[36:37], v[2:3] op_sel_hi:[0,1]
	v_cvt_pk_bf16_f32 v0, v0, v1
	v_cvt_pk_bf16_f32 v1, v2, v3
	global_store_dwordx2 v[32:33], v[0:1], off offset:112
	s_barrier
	s_cbranch_vccz .LBB0_871
.LBB0_865:
	s_add_i32 s34, s8, s66
	s_cmpk_gt_i32 s34, 0x3ff
	s_cselect_b32 s67, 1, 0
	s_and_b32 s68, s34, 0x60
	s_cselect_b32 s68, 0, 1
	s_cmp_eq_u32 s28, 0x100
	s_cselect_b32 s67, s68, s67
	s_cmp_lg_u32 s67, 0
	s_cselect_b64 s[38:39], -1, 0
	v_add_u32_e32 v0, v105, v131
	s_and_b64 vcc, exec, s[38:39]
	s_ashr_i32 s40, s8, 9
	s_ashr_i32 s41, s40, 31
	s_lshl_b32 s0, s8, 7
	s_and_b32 s0, s0, 0x1f80
	s_lshl_b64 s[40:41], s[40:41], 13
	s_or_b32 s0, s40, s0
	v_mov_b32_e32 v45, s41
	v_or_b32_e32 v44, s0, v120
	s_bfe_u32 s57, s8, 0x30006
	v_lshlrev_b64 v[44:45], 10, v[44:45]
	v_mov_b32_e32 v42, v44
	v_mov_b32_e32 v43, v45
	v_lshl_add_u64 v[44:45], s[10:11], 0, v[44:45]
	s_lshl_b32 s0, s57, 7
	v_lshl_add_u64 v[42:43], v[124:125], 0, v[42:43]
	v_lshl_add_u64 v[42:43], v[42:43], 0, s[0:1]
	v_lshlrev_b64 v[42:43], 1, v[42:43]
	v_lshl_add_u64 v[42:43], s[16:17], 0, v[42:43]
	global_load_dwordx2 v[226:227], v[42:43], off
	global_load_dwordx2 v[228:229], v[42:43], off offset:16
	global_load_dwordx2 v[230:231], v[42:43], off offset:32
	global_load_dwordx2 v[232:233], v[42:43], off offset:48
	global_load_dwordx2 v[234:235], v[42:43], off offset:64
	global_load_dwordx2 v[236:237], v[42:43], off offset:80
	global_load_dwordx2 v[238:239], v[42:43], off offset:96
	global_load_dwordx2 v[240:241], v[42:43], off offset:112
	v_lshl_add_u64 v[44:45], v[44:45], 0, s[0:1]
	v_lshl_add_u64 v[44:45], v[44:45], 0, v[108:109]
	global_load_dwordx4 v[88:91], v[44:45], off
	global_load_dwordx4 v[92:95], v[44:45], off offset:32
	s_lshl_b32 s57, s57, 2
	v_mov_b32_e32 v46, s57
	global_load_dword v128, v46, s[50:51]
	global_load_dword v129, v46, s[52:53]
	global_load_dwordx4 v[96:99], v[44:45], off offset:64
	global_load_dwordx4 v[100:103], v[44:45], off offset:96
	s_waitcnt vmcnt(23)
	ds_write_b128 v134, v[48:51]
	s_waitcnt vmcnt(17)
	ds_write_b128 v134, v[72:75] offset:53248
	s_waitcnt vmcnt(16)
	ds_write_b128 v135, v[76:79]
	ds_write_b128 v134, v[52:55] offset:9216
	s_waitcnt vmcnt(15)
	ds_write_b128 v134, v[80:83] offset:62464
	s_waitcnt vmcnt(14)
	ds_write_b128 v135, v[84:87] offset:9216
	ds_write_b16 v0, v56 offset:18432
	ds_write_b16_d16_hi v0, v56 offset:18704
	ds_write_b16 v0, v57 offset:18976
	ds_write_b16_d16_hi v0, v57 offset:19248
	ds_write_b16 v0, v58 offset:19520
	ds_write_b16_d16_hi v0, v58 offset:19792
	ds_write_b16 v0, v59 offset:20064
	ds_write_b16_d16_hi v0, v59 offset:20336
	ds_write_b16 v136, v60 offset:18432
	ds_write_b16_d16_hi v136, v60 offset:18704
	ds_write_b16 v136, v61 offset:18976
	ds_write_b16_d16_hi v136, v61 offset:19248
	ds_write_b16 v136, v62 offset:19520
	ds_write_b16_d16_hi v136, v62 offset:19792
	ds_write_b16 v136, v63 offset:20064
	ds_write_b16_d16_hi v136, v63 offset:20336
	ds_write_b16 v136, v64 offset:27136
	ds_write_b16_d16_hi v136, v64 offset:27408
	ds_write_b16 v136, v65 offset:27680
	ds_write_b16_d16_hi v136, v65 offset:27952
	ds_write_b16 v136, v66 offset:28224
	ds_write_b16_d16_hi v136, v66 offset:28496
	ds_write_b16 v136, v67 offset:28768
	ds_write_b16_d16_hi v136, v67 offset:29040
	ds_write_b16 v136, v68 offset:35840
	ds_write_b16_d16_hi v136, v68 offset:36112
	ds_write_b16 v136, v69 offset:36384
	ds_write_b16_d16_hi v136, v69 offset:36656
	ds_write_b16 v136, v70 offset:36928
	ds_write_b16_d16_hi v136, v70 offset:37200
	ds_write_b16 v136, v71 offset:37472
	ds_write_b16_d16_hi v136, v71 offset:37744
	s_waitcnt lgkmcnt(0)
	s_barrier
	s_waitcnt vmcnt(0)
	s_cbranch_vccnz .LBB0_867
	s_ashr_i32 s40, s34, 9
	s_and_b32 s0, s34, 63
	s_ashr_i32 s41, s40, 31
	s_lshl_b64 s[40:41], s[40:41], 13
	s_lshl_b32 s0, s0, 7
	s_bfe_u32 s9, s34, 0x30006
	s_or_b32 s40, s40, s0
	v_lshl_add_u64 v[0:1], s[40:41], 0, v[106:107]
	s_lshl_b32 s0, s9, 7
	v_lshl_add_u64 v[2:3], v[116:117], 0, s[0:1]
	v_lshlrev_b64 v[0:1], 10, v[0:1]
	v_lshl_add_u64 v[0:1], v[2:3], 0, v[0:1]
	v_add_co_u32_e32 v2, vcc, s23, v0
	s_lshl_b32 s0, s9, 8
	s_nop 0
	v_addc_co_u32_e32 v3, vcc, 0, v1, vcc
	global_load_dwordx4 v[48:51], v[0:1], off
	global_load_dwordx4 v[52:55], v[2:3], off
	v_mov_b32_e32 v1, s41
	v_or_b32_e32 v0, s40, v104
	v_lshlrev_b64 v[0:1], 11, v[0:1]
	v_lshl_add_u64 v[0:1], s[12:13], 0, v[0:1]
	v_lshl_add_u64 v[0:1], v[0:1], 0, s[0:1]
	s_ashr_i32 s35, s34, 31
	s_add_i32 s46, s34, 0x400
	v_lshl_add_u64 v[0:1], v[110:111], 1, v[0:1]
	s_lshl_b64 s[40:41], s[34:35], 14
	s_ashr_i32 s47, s46, 31
	global_load_dwordx4 v[56:59], v[0:1], off
	global_load_dwordx4 v[60:63], v[0:1], off offset:64
	global_load_dwordx4 v[64:67], v[0:1], off offset:128
	global_load_dwordx4 v[68:71], v[0:1], off offset:192
	s_lshl_b64 s[46:47], s[46:47], 14
	v_lshl_add_u64 v[0:1], v[118:119], 0, s[40:41]
	v_lshl_add_u64 v[2:3], v[118:119], 0, s[46:47]
	v_lshl_add_u64 v[4:5], v[0:1], 0, v[112:113]
	v_lshl_add_u64 v[0:1], v[0:1], 0, v[114:115]
	v_lshl_add_u64 v[6:7], v[2:3], 0, v[112:113]
	global_load_dwordx4 v[72:75], v[4:5], off
	global_load_dwordx4 v[76:79], v[6:7], off
	v_lshl_add_u64 v[2:3], v[2:3], 0, v[114:115]
	global_load_dwordx4 v[80:83], v[0:1], off
	global_load_dwordx4 v[84:87], v[2:3], off
.LBB0_867:
	s_ashr_i32 s40, s8, 9
	s_ashr_i32 s41, s40, 31
	s_lshl_b32 s0, s8, 7
	s_and_b32 s0, s0, 0x1f80
	s_lshl_b64 s[40:41], s[40:41], 13
	s_or_b32 s0, s40, s0
	v_mov_b32_e32 v1, s41
	v_or_b32_e32 v0, s0, v120
	s_bfe_u32 s8, s8, 0x30006
	v_lshlrev_b64 v[126:127], 10, v[0:1]
	v_lshl_add_u64 v[0:1], s[10:11], 0, v[126:127]
	s_lshl_b32 s0, s8, 7
	v_lshl_add_u64 v[0:1], v[0:1], 0, s[0:1]
	v_lshl_add_u64 v[40:41], v[0:1], 0, v[108:109]
	s_lshl_b32 s8, s8, 2
	v_mov_b32_e32 v0, s8
	ds_read_b128 v[0:3], v137 offset:53248
	ds_read_b128 v[32:35], v137 offset:53280
	ds_read_b128 v[16:19], v137 offset:57856
	ds_read_b128 v[36:39], v137 offset:57888
	ds_read_b128 v[40:43], v137 offset:53312
	ds_read_b128 v[44:47], v137 offset:53344
	s_mov_b32 s35, 0
	s_waitcnt lgkmcnt(5)
	v_mfma_f32_32x32x16_bf16 v[0:15], v[0:3], v[88:91], 0
	v_mul_f32_e32 v146, 0x3fb8aa3b, v128
	v_mul_f32_e32 v147, 0x3fb8aa3b, v129
	v_fma_f32 v148, v128, s3, -v146
	v_rndne_f32_e32 v149, v146
	v_fma_f32 v150, v129, s3, -v147
	s_waitcnt lgkmcnt(3)
	v_mfma_f32_32x32x16_bf16 v[16:31], v[16:19], v[88:91], 0
	v_fmac_f32_e32 v148, 0x32a5705f, v128
	v_fmac_f32_e32 v150, 0x32a5705f, v129
	v_cmp_ngt_f32_e32 vcc, s42, v128
	v_mfma_f32_32x32x16_bf16 v[0:15], v[32:35], v[92:95], v[0:15]
	ds_read_b128 v[32:35], v137 offset:57920
	ds_read_b128 v[142:145], v137 offset:57952
	s_waitcnt lgkmcnt(4)
	v_mfma_f32_32x32x16_bf16 v[16:31], v[36:39], v[92:95], v[16:31]
	v_rndne_f32_e32 v36, v147
	v_sub_f32_e32 v37, v146, v149
	v_sub_f32_e32 v39, v147, v36
	v_add_f32_e32 v37, v37, v148
	v_cvt_i32_f32_e32 v38, v149
	v_add_f32_e32 v39, v39, v150
	v_exp_f32_e32 v37, v37
	s_waitcnt lgkmcnt(3)
	v_mfma_f32_32x32x16_bf16 v[0:15], v[40:43], v[96:99], v[0:15]
	v_cvt_i32_f32_e32 v36, v36
	v_exp_f32_e32 v39, v39
	v_ldexp_f32 v37, v37, v38
	ds_read_b128 v[146:149], v138
	ds_read_b128 v[150:153], v138 offset:32
	ds_read_b128 v[154:157], v138 offset:4608
	ds_read_b128 v[158:161], v138 offset:4640
	s_waitcnt lgkmcnt(5)
	v_mfma_f32_32x32x16_bf16 v[16:31], v[32:35], v[96:99], v[16:31]
	v_ldexp_f32 v32, v39, v36
	v_cndmask_b32_e32 v33, 0, v37, vcc
	v_cmp_ngt_f32_e32 vcc, s42, v129
	s_nop 1
	v_cndmask_b32_e32 v34, 0, v32, vcc
	v_cmp_nlt_f32_e32 vcc, s43, v128
	v_mfma_f32_32x32x16_bf16 v[0:15], v[44:47], v[100:103], v[0:15]
	v_cndmask_b32_e32 v32, v141, v33, vcc
	v_cmp_nlt_f32_e32 vcc, s43, v129
	s_nop 1
	v_cndmask_b32_e32 v33, v141, v34, vcc
	v_mul_f32_e64 v128, v32, s22
	v_mul_f32_e64 v129, v33, s22
	s_waitcnt lgkmcnt(4)
	v_mfma_f32_32x32x16_bf16 v[16:31], v[142:145], v[100:103], v[16:31]
	v_mul_f32_e64 v162, v128, v122
	v_mul_f32_e64 v163, v129, v123
	v_mov_b32_e32 v142, v121
	v_sub_f32_e32 v32, v162, v163
	v_exp_f32_e32 v162, v32
	v_mov_b32_e32 v143, v133
	v_pk_mul_f32 v[32:33], v[162:163], v[0:1] op_sel_hi:[0,1]
	v_pk_mul_f32 v[46:47], v[162:163], v[14:15] op_sel_hi:[0,1]
	v_pk_mul_f32 v[44:45], v[162:163], v[12:13] op_sel_hi:[0,1]
	v_pk_mul_f32 v[42:43], v[162:163], v[10:11] op_sel_hi:[0,1]
	v_pk_mul_f32 v[40:41], v[162:163], v[8:9] op_sel_hi:[0,1]
	v_pk_mul_f32 v[38:39], v[162:163], v[6:7] op_sel_hi:[0,1]
	v_pk_mul_f32 v[36:37], v[162:163], v[4:5] op_sel_hi:[0,1]
	v_pk_mul_f32 v[34:35], v[162:163], v[2:3] op_sel_hi:[0,1]
	v_pk_mul_f32 v[0:1], v[162:163], v[16:17] op_sel_hi:[0,1]
	v_pk_mul_f32 v[14:15], v[162:163], v[30:31] op_sel_hi:[0,1]
	s_waitcnt lgkmcnt(3)
	v_mfma_f32_32x32x16_bf16 v[32:47], v[146:149], v[88:91], v[32:47]
	v_mul_f32_e64 v12, v162, v28
	v_mul_f32_e64 v13, v162, v29
	v_mul_f32_e64 v10, v162, v26
	v_mul_f32_e64 v11, v162, v27
	v_mul_f32_e64 v8, v162, v24
	v_mul_f32_e64 v9, v162, v25
	v_pk_mul_f32 v[6:7], v[162:163], v[22:23] op_sel_hi:[0,1]
	v_pk_mul_f32 v[4:5], v[162:163], v[20:21] op_sel_hi:[0,1]
	v_pk_mul_f32 v[2:3], v[162:163], v[18:19] op_sel_hi:[0,1]
	ds_read_b128 v[16:19], v138 offset:64
	ds_read_b128 v[20:23], v138 offset:96
	s_waitcnt lgkmcnt(3)
	v_mfma_f32_32x32x16_bf16 v[0:15], v[154:157], v[88:91], v[0:15]
	v_mfma_f32_32x32x16_bf16 v[32:47], v[150:153], v[92:95], v[32:47]
	s_waitcnt lgkmcnt(2)
	v_mfma_f32_32x32x16_bf16 v[0:15], v[158:161], v[92:95], v[0:15]
	s_waitcnt lgkmcnt(1)
	v_mfma_f32_32x32x16_bf16 v[32:47], v[16:19], v[96:99], v[32:47]
	ds_read_b128 v[16:19], v138 offset:4672
	ds_read_b128 v[24:27], v138 offset:4704
	s_waitcnt lgkmcnt(1)
	v_mfma_f32_32x32x16_bf16 v[0:15], v[16:19], v[96:99], v[0:15]
	v_exp_f32_e32 v16, v163
	v_mfma_f32_32x32x16_bf16 v[32:47], v[20:23], v[100:103], v[32:47]
	s_waitcnt lgkmcnt(0)
	v_mfma_f32_32x32x16_bf16 v[0:15], v[24:27], v[100:103], v[0:15]
	s_nop 9
	v_mul_f32_e64 v30, v16, v46
	v_mul_f32_e64 v31, v16, v47
	v_mul_f32_e64 v28, v16, v44
	v_mul_f32_e64 v29, v16, v45
	v_mul_f32_e64 v26, v16, v42
	v_mul_f32_e64 v27, v16, v43
	v_pk_mul_f32 v[24:25], v[16:17], v[40:41] op_sel_hi:[0,1]
	v_pk_mul_f32 v[22:23], v[16:17], v[38:39] op_sel_hi:[0,1]
	v_pk_mul_f32 v[20:21], v[16:17], v[36:37] op_sel_hi:[0,1]
	v_pk_mul_f32 v[18:19], v[16:17], v[34:35] op_sel_hi:[0,1]
	v_pk_mul_f32 v[14:15], v[16:17], v[14:15] op_sel_hi:[0,1]
	v_pk_mul_f32 v[12:13], v[16:17], v[12:13] op_sel_hi:[0,1]
	v_pk_mul_f32 v[10:11], v[16:17], v[10:11] op_sel_hi:[0,1]
	v_pk_mul_f32 v[8:9], v[16:17], v[8:9] op_sel_hi:[0,1]
	v_pk_mul_f32 v[6:7], v[16:17], v[6:7] op_sel_hi:[0,1]
	v_pk_mul_f32 v[4:5], v[16:17], v[4:5] op_sel_hi:[0,1]
	v_pk_mul_f32 v[2:3], v[16:17], v[2:3] op_sel_hi:[0,1]
	v_pk_mul_f32 v[0:1], v[16:17], v[0:1] op_sel_hi:[0,1]
	v_pk_mul_f32 v[16:17], v[16:17], v[32:33] op_sel_hi:[0,1]
	s_lshl_b32 s56, s33, 4
	s_add_i32 s56, s56, 0x18000
	v_and_b32_e32 v34, 63, v104
	v_sub_u32_e32 v35, 0x7f, v34
	v_subrev_u32_e32 v36, 63, v34
	v_sub_u32_e32 v37, 63, v34
	v_add_u32_e32 v38, 1, v34
	v_add_u32_e32 v39, 0x41, v34
	v_max_i32_e32 v37, v36, v37
	v_cmp_gt_i32_e32 vcc, 0, v36
	v_cvt_f32_u32_e32 v35, v35
	v_cvt_f32_u32_e32 v37, v37
	v_cvt_f32_u32_e32 v38, v38
	v_cvt_f32_u32_e32 v39, v39
	v_cndmask_b32_e32 v36, v128, v129, vcc
	v_mul_f32_e32 v35, v129, v35
	v_mul_f32_e32 v36, v36, v37
	v_mul_f32_e32 v38, v128, v38
	v_mul_f32_e32 v39, v128, v39
	v_exp_f32_e32 v35, v35
	v_exp_f32_e32 v36, v36
	v_exp_f32_e32 v38, v38
	v_exp_f32_e32 v39, v39
	v_lshl_add_u32 v40, v34, 2, s56
	v_add_u32_e32 v224, 4, v132
	v_lshl_add_u32 v224, v224, 2, s56
	ds_write_b32 v40, v35
	ds_write_b32 v40, v36 offset:256
	ds_write_b32 v40, v38 offset:512
	ds_write_b32 v40, v39 offset:768
	ds_read_b128 v[144:147], v142
	ds_read_b128 v[148:151], v142 offset:32
	ds_read_b128 v[152:155], v142 offset:64
	ds_read_b128 v[156:159], v142 offset:96
	ds_read_b32 v160, v224 offset:492
	ds_read_b32 v161, v224 offset:488
	ds_read_b32 v162, v224 offset:484
	ds_read_b32 v163, v224 offset:480
	ds_read_b32 v164, v224 offset:460
	ds_read_b32 v165, v224 offset:456
	ds_read_b32 v166, v224 offset:452
	ds_read_b32 v167, v224 offset:448
	ds_read_b32 v168, v224 offset:428
	ds_read_b32 v169, v224 offset:424
	ds_read_b32 v170, v224 offset:420
	ds_read_b32 v171, v224 offset:416
	ds_read_b32 v172, v224 offset:396
	ds_read_b32 v173, v224 offset:392
	ds_read_b32 v174, v224 offset:388
	ds_read_b32 v175, v224 offset:384
	s_waitcnt lgkmcnt(0)
	v_mfma_f32_32x32x16_bf16 v[32:47], v[144:147], v[88:91], 0
	v_mfma_f32_32x32x16_bf16 v[32:47], v[148:151], v[92:95], v[32:47]
	v_mfma_f32_32x32x16_bf16 v[32:47], v[152:155], v[96:99], v[32:47]
	v_mfma_f32_32x32x16_bf16 v[32:47], v[156:159], v[100:103], v[32:47]
	ds_read_b128 v[144:147], v142 offset:4608
	ds_read_b128 v[148:151], v142 offset:4640
	ds_read_b128 v[152:155], v142 offset:4672
	ds_read_b128 v[156:159], v142 offset:4704
	ds_read_b32 v176, v224 offset:364
	ds_read_b32 v177, v224 offset:360
	ds_read_b32 v178, v224 offset:356
	ds_read_b32 v179, v224 offset:352
	ds_read_b32 v180, v224 offset:332
	ds_read_b32 v181, v224 offset:328
	ds_read_b32 v182, v224 offset:324
	ds_read_b32 v183, v224 offset:320
	ds_read_b32 v184, v224 offset:300
	ds_read_b32 v185, v224 offset:296
	ds_read_b32 v186, v224 offset:292
	ds_read_b32 v187, v224 offset:288
	ds_read_b32 v188, v224 offset:268
	ds_read_b32 v189, v224 offset:264
	ds_read_b32 v190, v224 offset:260
	ds_read_b32 v191, v224 offset:256
	ds_read_b128 v[208:211], v143
	ds_read_b128 v[212:215], v143 offset:8704
	ds_read_b128 v[216:219], v143 offset:32
	ds_read_b128 v[220:223], v143 offset:8736
	s_waitcnt lgkmcnt(15)
	v_mfma_f32_32x32x16_bf16 v[192:207], v[144:147], v[88:91], 0
	v_mfma_f32_32x32x16_bf16 v[192:207], v[148:151], v[92:95], v[192:207]
	v_mfma_f32_32x32x16_bf16 v[192:207], v[152:155], v[96:99], v[192:207]
	v_mfma_f32_32x32x16_bf16 v[192:207], v[156:159], v[100:103], v[192:207]
	s_waitcnt lgkmcnt(0)
	v_pk_mul_f32 v[32:33], v[160:161], v[32:33]
	v_pk_mul_f32 v[34:35], v[162:163], v[34:35]
	v_pk_mul_f32 v[36:37], v[164:165], v[36:37]
	v_pk_mul_f32 v[38:39], v[166:167], v[38:39]
	v_pk_mul_f32 v[40:41], v[168:169], v[40:41]
	v_pk_mul_f32 v[42:43], v[170:171], v[42:43]
	v_pk_mul_f32 v[44:45], v[172:173], v[44:45]
	v_pk_mul_f32 v[46:47], v[174:175], v[46:47]
	v_cvt_pk_bf16_f32 v32, v32, v33
	v_cvt_pk_bf16_f32 v33, v34, v35
	v_cvt_pk_bf16_f32 v34, v36, v37
	v_cvt_pk_bf16_f32 v35, v38, v39
	v_cvt_pk_bf16_f32 v36, v40, v41
	v_cvt_pk_bf16_f32 v37, v42, v43
	v_cvt_pk_bf16_f32 v38, v44, v45
	v_cvt_pk_bf16_f32 v39, v46, v47
	s_nop 1
	v_mfma_f32_32x32x16_bf16 v[16:31], v[208:211], v[32:35], v[16:31]
	v_mfma_f32_32x32x16_bf16 v[0:15], v[212:215], v[32:35], v[0:15]
	v_mfma_f32_32x32x16_bf16 v[16:31], v[216:219], v[36:39], v[16:31]
	v_mfma_f32_32x32x16_bf16 v[0:15], v[220:223], v[36:39], v[0:15]
	ds_read_b128 v[144:147], v142 offset:9216
	ds_read_b128 v[148:151], v142 offset:9248
	ds_read_b128 v[152:155], v142 offset:9280
	ds_read_b128 v[156:159], v142 offset:9312
	ds_read_b32 v160, v224 offset:236
	ds_read_b32 v161, v224 offset:232
	ds_read_b32 v162, v224 offset:228
	ds_read_b32 v163, v224 offset:224
	ds_read_b32 v164, v224 offset:204
	ds_read_b32 v165, v224 offset:200
	ds_read_b32 v166, v224 offset:196
	ds_read_b32 v167, v224 offset:192
	ds_read_b32 v168, v224 offset:172
	ds_read_b32 v169, v224 offset:168
	ds_read_b32 v170, v224 offset:164
	ds_read_b32 v171, v224 offset:160
	ds_read_b32 v172, v224 offset:140
	ds_read_b32 v173, v224 offset:136
	ds_read_b32 v174, v224 offset:132
	ds_read_b32 v175, v224 offset:128
	ds_read_b128 v[208:211], v143 offset:64
	ds_read_b128 v[212:215], v143 offset:8768
	ds_read_b128 v[216:219], v143 offset:96
	ds_read_b128 v[220:223], v143 offset:8800
	s_waitcnt lgkmcnt(15)
	v_mfma_f32_32x32x16_bf16 v[32:47], v[144:147], v[88:91], 0
	v_mfma_f32_32x32x16_bf16 v[32:47], v[148:151], v[92:95], v[32:47]
	v_mfma_f32_32x32x16_bf16 v[32:47], v[152:155], v[96:99], v[32:47]
	v_mfma_f32_32x32x16_bf16 v[32:47], v[156:159], v[100:103], v[32:47]
	s_waitcnt lgkmcnt(0)
	v_pk_mul_f32 v[192:193], v[176:177], v[192:193]
	v_pk_mul_f32 v[194:195], v[178:179], v[194:195]
	v_pk_mul_f32 v[196:197], v[180:181], v[196:197]
	v_pk_mul_f32 v[198:199], v[182:183], v[198:199]
	v_pk_mul_f32 v[200:201], v[184:185], v[200:201]
	v_pk_mul_f32 v[202:203], v[186:187], v[202:203]
	v_pk_mul_f32 v[204:205], v[188:189], v[204:205]
	v_pk_mul_f32 v[206:207], v[190:191], v[206:207]
	v_cvt_pk_bf16_f32 v192, v192, v193
	v_cvt_pk_bf16_f32 v193, v194, v195
	v_cvt_pk_bf16_f32 v194, v196, v197
	v_cvt_pk_bf16_f32 v195, v198, v199
	v_cvt_pk_bf16_f32 v196, v200, v201
	v_cvt_pk_bf16_f32 v197, v202, v203
	v_cvt_pk_bf16_f32 v198, v204, v205
	v_cvt_pk_bf16_f32 v199, v206, v207
	s_nop 1
	v_mfma_f32_32x32x16_bf16 v[16:31], v[208:211], v[192:195], v[16:31]
	v_mfma_f32_32x32x16_bf16 v[0:15], v[212:215], v[192:195], v[0:15]
	v_mfma_f32_32x32x16_bf16 v[16:31], v[216:219], v[196:199], v[16:31]
	v_mfma_f32_32x32x16_bf16 v[0:15], v[220:223], v[196:199], v[0:15]
	ds_read_b128 v[144:147], v142 offset:13824
	ds_read_b128 v[148:151], v142 offset:13856
	ds_read_b128 v[152:155], v142 offset:13888
	ds_read_b128 v[156:159], v142 offset:13920
	ds_read_b32 v176, v224 offset:108
	ds_read_b32 v177, v224 offset:104
	ds_read_b32 v178, v224 offset:100
	ds_read_b32 v179, v224 offset:96
	ds_read_b32 v180, v224 offset:76
	ds_read_b32 v181, v224 offset:72
	ds_read_b32 v182, v224 offset:68
	ds_read_b32 v183, v224 offset:64
	ds_read_b32 v184, v224 offset:44
	ds_read_b32 v185, v224 offset:40
	ds_read_b32 v186, v224 offset:36
	ds_read_b32 v187, v224 offset:32
	ds_read_b32 v188, v224 offset:12
	ds_read_b32 v189, v224 offset:8
	ds_read_b32 v190, v224 offset:4
	ds_read_b32 v191, v224
	ds_read_b128 v[208:211], v143 offset:128
	ds_read_b128 v[212:215], v143 offset:8832
	ds_read_b128 v[216:219], v143 offset:160
	ds_read_b128 v[220:223], v143 offset:8864
	s_waitcnt lgkmcnt(15)
	v_mfma_f32_32x32x16_bf16 v[192:207], v[144:147], v[88:91], 0
	v_mfma_f32_32x32x16_bf16 v[192:207], v[148:151], v[92:95], v[192:207]
	v_mfma_f32_32x32x16_bf16 v[192:207], v[152:155], v[96:99], v[192:207]
	v_mfma_f32_32x32x16_bf16 v[192:207], v[156:159], v[100:103], v[192:207]
	s_waitcnt lgkmcnt(0)
	v_pk_mul_f32 v[32:33], v[160:161], v[32:33]
	v_pk_mul_f32 v[34:35], v[162:163], v[34:35]
	v_pk_mul_f32 v[36:37], v[164:165], v[36:37]
	v_pk_mul_f32 v[38:39], v[166:167], v[38:39]
	v_pk_mul_f32 v[40:41], v[168:169], v[40:41]
	v_pk_mul_f32 v[42:43], v[170:171], v[42:43]
	v_pk_mul_f32 v[44:45], v[172:173], v[44:45]
	v_pk_mul_f32 v[46:47], v[174:175], v[46:47]
	v_cvt_pk_bf16_f32 v32, v32, v33
	v_cvt_pk_bf16_f32 v33, v34, v35
	v_cvt_pk_bf16_f32 v34, v36, v37
	v_cvt_pk_bf16_f32 v35, v38, v39
	v_cvt_pk_bf16_f32 v36, v40, v41
	v_cvt_pk_bf16_f32 v37, v42, v43
	v_cvt_pk_bf16_f32 v38, v44, v45
	v_cvt_pk_bf16_f32 v39, v46, v47
	s_nop 1
	v_mfma_f32_32x32x16_bf16 v[16:31], v[208:211], v[32:35], v[16:31]
	v_mfma_f32_32x32x16_bf16 v[0:15], v[212:215], v[32:35], v[0:15]
	v_mfma_f32_32x32x16_bf16 v[16:31], v[216:219], v[36:39], v[16:31]
	v_mfma_f32_32x32x16_bf16 v[0:15], v[220:223], v[36:39], v[0:15]
	ds_read_b128 v[208:211], v143 offset:192
	ds_read_b128 v[212:215], v143 offset:8896
	ds_read_b128 v[216:219], v143 offset:224
	ds_read_b128 v[220:223], v143 offset:8928
	s_waitcnt lgkmcnt(0)
	v_pk_mul_f32 v[192:193], v[176:177], v[192:193]
	v_pk_mul_f32 v[194:195], v[178:179], v[194:195]
	v_pk_mul_f32 v[196:197], v[180:181], v[196:197]
	v_pk_mul_f32 v[198:199], v[182:183], v[198:199]
	v_pk_mul_f32 v[200:201], v[184:185], v[200:201]
	v_pk_mul_f32 v[202:203], v[186:187], v[202:203]
	v_pk_mul_f32 v[204:205], v[188:189], v[204:205]
	v_pk_mul_f32 v[206:207], v[190:191], v[206:207]
	v_cvt_pk_bf16_f32 v192, v192, v193
	v_cvt_pk_bf16_f32 v193, v194, v195
	v_cvt_pk_bf16_f32 v194, v196, v197
	v_cvt_pk_bf16_f32 v195, v198, v199
	v_cvt_pk_bf16_f32 v196, v200, v201
	v_cvt_pk_bf16_f32 v197, v202, v203
	v_cvt_pk_bf16_f32 v198, v204, v205
	v_cvt_pk_bf16_f32 v199, v206, v207
	s_nop 1
	v_mfma_f32_32x32x16_bf16 v[16:31], v[208:211], v[192:195], v[16:31]
	v_mfma_f32_32x32x16_bf16 v[0:15], v[212:215], v[192:195], v[0:15]
	v_mfma_f32_32x32x16_bf16 v[16:31], v[216:219], v[196:199], v[16:31]
	v_mfma_f32_32x32x16_bf16 v[0:15], v[220:223], v[196:199], v[0:15]
	s_movk_i32 s35, 0xff80
	s_nop 3
	s_nop 6
	v_mul_f32_e32 v32, v17, v17
	v_fmac_f32_e32 v32, v16, v16
	v_fmac_f32_e32 v32, v18, v18
	v_fmac_f32_e32 v32, v19, v19
	v_fmac_f32_e32 v32, v20, v20
	v_fmac_f32_e32 v32, v21, v21
	v_fmac_f32_e32 v32, v22, v22
	v_fmac_f32_e32 v32, v23, v23
	v_fmac_f32_e32 v32, v24, v24
	v_fmac_f32_e32 v32, v25, v25
	v_fmac_f32_e32 v32, v26, v26
	v_fmac_f32_e32 v32, v27, v27
	v_fmac_f32_e32 v32, v28, v28
	v_fmac_f32_e32 v32, v29, v29
	v_fmac_f32_e32 v32, v30, v30
	v_fmac_f32_e32 v32, v31, v31
	v_fmac_f32_e32 v32, v0, v0
	v_fmac_f32_e32 v32, v1, v1
	v_fmac_f32_e32 v32, v2, v2
	v_fmac_f32_e32 v32, v3, v3
	v_fmac_f32_e32 v32, v4, v4
	v_fmac_f32_e32 v32, v5, v5
	v_fmac_f32_e32 v32, v6, v6
	v_fmac_f32_e32 v32, v7, v7
	v_fmac_f32_e32 v32, v8, v8
	v_fmac_f32_e32 v32, v9, v9
	v_fmac_f32_e32 v32, v10, v10
	v_fmac_f32_e32 v32, v11, v11
	v_fmac_f32_e32 v32, v12, v12
	v_fmac_f32_e32 v32, v13, v13
	v_fmac_f32_e32 v32, v14, v14
	v_fmac_f32_e32 v32, v15, v15
	v_mov_b32_e32 v33, v32
	s_nop 1
	v_permlane32_swap_b32_e32 v32, v33
	v_add_f32_e32 v36, v32, v33
	s_and_saveexec_b64 s[40:41], s[6:7]
	s_cbranch_execz .LBB0_864
	ds_write_b32 v139, v36
	s_branch .LBB0_864
